# attn0 window epilogue: 16 output read-modify-write round trips issued together with counted vmcnt instead of serial load-wait-fma-store
# speedup vs baseline: 1.0106x; 1.0001x over previous
.LBB0_1696:
	v_lshl_add_u32 v2, s22, 13, v176
	v_mov_b64_e32 v[4:5], s[0:1]
	s_movk_i32 s2, 0x60
	v_mad_i64_i32 v[4:5], s[2:3], v2, s2, v[4:5]
	s_mul_i32 s84, s21, 12
	v_lshl_add_u64 v[4:5], v[4:5], 0, s[84:85]
	s_mov_b32 s2, 0x14968000
	v_add_co_u32_e32 v4, vcc, s2, v4
	v_mov_b32_e32 v1, v177
	s_nop 0
	v_addc_co_u32_e32 v5, vcc, 0, v5, vcc
	global_load_dword v4, v[4:5], off offset:2056
	v_ashrrev_i32_e32 v3, 31, v2
	v_lshlrev_b64 v[2:3], 12, v[2:3]
	v_lshlrev_b32_e32 v10, 2, v180
	v_mov_b32_e32 v11, v0
	v_lshl_add_u64 v[2:3], s[10:11], 0, v[2:3]
	s_lshl_b32 s84, s21, 9
	s_nop 0
	v_lshl_add_u64 v[2:3], v[2:3], 0, s[84:85]
	s_nop 0
	v_lshl_add_u64 v[12:13], v[2:3], 0, v[10:11]
	s_nop 1
	global_load_dwordx4 v[80:83], v[12:13], off
	global_load_dwordx4 v[84:87], v[12:13], off offset:32
	global_load_dwordx4 v[88:91], v[12:13], off offset:64
	global_load_dwordx4 v[92:95], v[12:13], off offset:96
	global_load_dwordx4 v[96:99], v[12:13], off offset:128
	global_load_dwordx4 v[100:103], v[12:13], off offset:160
	global_load_dwordx4 v[104:107], v[12:13], off offset:192
	global_load_dwordx4 v[108:111], v[12:13], off offset:224
	global_load_dwordx4 v[144:147], v[12:13], off offset:256
	global_load_dwordx4 v[148:151], v[12:13], off offset:288
	global_load_dwordx4 v[152:155], v[12:13], off offset:320
	global_load_dwordx4 v[156:159], v[12:13], off offset:352
	global_load_dwordx4 v[160:163], v[12:13], off offset:384
	global_load_dwordx4 v[164:167], v[12:13], off offset:416
	global_load_dwordx4 v[168:171], v[12:13], off offset:448
	global_load_dwordx4 v[172:175], v[12:13], off offset:480
	v_permlane32_swap_b32_e32 v177, v1
	v_add_f32_e32 v1, v177, v1
	v_div_scale_f32 v5, s[4:5], v1, v1, 1.0
	v_rcp_f32_e32 v6, v5
	v_cmp_lt_f32_e64 s[2:3], 0, v1
	s_nop 0
	v_fma_f32 v7, -v5, v6, 1.0
	v_fmac_f32_e32 v6, v7, v6
	v_div_scale_f32 v7, vcc, 1.0, v1, 1.0
	v_mul_f32_e32 v8, v7, v6
	v_fma_f32 v9, -v5, v8, v7
	v_fmac_f32_e32 v8, v9, v6
	v_fma_f32 v5, -v5, v8, v7
	v_div_fmas_f32 v5, v5, v6, v8
	v_div_fixup_f32 v1, v5, v1, 1.0
	s_nop 0
	v_cndmask_b32_e64 v1, 0, v1, s[2:3]
	s_waitcnt vmcnt(16)
	v_mul_f32_e32 v6, v4, v1
	s_waitcnt vmcnt(15)
	v_pk_fma_f32 v[80:81], v[64:65], v[6:7], v[80:81] op_sel_hi:[1,0,1]
	v_pk_fma_f32 v[82:83], v[66:67], v[6:7], v[82:83] op_sel_hi:[1,0,1]
	global_store_dwordx4 v[12:13], v[80:83], off
	s_waitcnt vmcnt(15)
	v_pk_fma_f32 v[84:85], v[68:69], v[6:7], v[84:85] op_sel_hi:[1,0,1]
	v_pk_fma_f32 v[86:87], v[70:71], v[6:7], v[86:87] op_sel_hi:[1,0,1]
	global_store_dwordx4 v[12:13], v[84:87], off offset:32
	s_waitcnt vmcnt(15)
	v_pk_fma_f32 v[88:89], v[72:73], v[6:7], v[88:89] op_sel_hi:[1,0,1]
	v_pk_fma_f32 v[90:91], v[74:75], v[6:7], v[90:91] op_sel_hi:[1,0,1]
	global_store_dwordx4 v[12:13], v[88:91], off offset:64
	s_waitcnt vmcnt(15)
	v_pk_fma_f32 v[92:93], v[76:77], v[6:7], v[92:93] op_sel_hi:[1,0,1]
	v_pk_fma_f32 v[94:95], v[78:79], v[6:7], v[94:95] op_sel_hi:[1,0,1]
	global_store_dwordx4 v[12:13], v[92:95], off offset:96
	s_waitcnt vmcnt(15)
	v_pk_fma_f32 v[96:97], v[48:49], v[6:7], v[96:97] op_sel_hi:[1,0,1]
	v_pk_fma_f32 v[98:99], v[50:51], v[6:7], v[98:99] op_sel_hi:[1,0,1]
	global_store_dwordx4 v[12:13], v[96:99], off offset:128
	s_waitcnt vmcnt(15)
	v_pk_fma_f32 v[100:101], v[52:53], v[6:7], v[100:101] op_sel_hi:[1,0,1]
	v_pk_fma_f32 v[102:103], v[54:55], v[6:7], v[102:103] op_sel_hi:[1,0,1]
	global_store_dwordx4 v[12:13], v[100:103], off offset:160
	s_waitcnt vmcnt(15)
	v_pk_fma_f32 v[104:105], v[56:57], v[6:7], v[104:105] op_sel_hi:[1,0,1]
	v_pk_fma_f32 v[106:107], v[58:59], v[6:7], v[106:107] op_sel_hi:[1,0,1]
	global_store_dwordx4 v[12:13], v[104:107], off offset:192
	s_waitcnt vmcnt(15)
	v_pk_fma_f32 v[108:109], v[60:61], v[6:7], v[108:109] op_sel_hi:[1,0,1]
	v_pk_fma_f32 v[110:111], v[62:63], v[6:7], v[110:111] op_sel_hi:[1,0,1]
	global_store_dwordx4 v[12:13], v[108:111], off offset:224
	s_waitcnt vmcnt(15)
	v_pk_fma_f32 v[144:145], v[32:33], v[6:7], v[144:145] op_sel_hi:[1,0,1]
	v_pk_fma_f32 v[146:147], v[34:35], v[6:7], v[146:147] op_sel_hi:[1,0,1]
	global_store_dwordx4 v[12:13], v[144:147], off offset:256
	s_waitcnt vmcnt(15)
	v_pk_fma_f32 v[148:149], v[36:37], v[6:7], v[148:149] op_sel_hi:[1,0,1]
	v_pk_fma_f32 v[150:151], v[38:39], v[6:7], v[150:151] op_sel_hi:[1,0,1]
	global_store_dwordx4 v[12:13], v[148:151], off offset:288
	s_waitcnt vmcnt(15)
	v_pk_fma_f32 v[152:153], v[40:41], v[6:7], v[152:153] op_sel_hi:[1,0,1]
	v_pk_fma_f32 v[154:155], v[42:43], v[6:7], v[154:155] op_sel_hi:[1,0,1]
	global_store_dwordx4 v[12:13], v[152:155], off offset:320
	s_waitcnt vmcnt(15)
	v_pk_fma_f32 v[156:157], v[44:45], v[6:7], v[156:157] op_sel_hi:[1,0,1]
	v_pk_fma_f32 v[158:159], v[46:47], v[6:7], v[158:159] op_sel_hi:[1,0,1]
	global_store_dwordx4 v[12:13], v[156:159], off offset:352
	s_waitcnt vmcnt(15)
	v_pk_fma_f32 v[160:161], v[16:17], v[6:7], v[160:161] op_sel_hi:[1,0,1]
	v_pk_fma_f32 v[162:163], v[18:19], v[6:7], v[162:163] op_sel_hi:[1,0,1]
	global_store_dwordx4 v[12:13], v[160:163], off offset:384
	s_waitcnt vmcnt(15)
	v_pk_fma_f32 v[164:165], v[20:21], v[6:7], v[164:165] op_sel_hi:[1,0,1]
	v_pk_fma_f32 v[166:167], v[22:23], v[6:7], v[166:167] op_sel_hi:[1,0,1]
	global_store_dwordx4 v[12:13], v[164:167], off offset:416
	s_waitcnt vmcnt(15)
	v_pk_fma_f32 v[168:169], v[24:25], v[6:7], v[168:169] op_sel_hi:[1,0,1]
	v_pk_fma_f32 v[170:171], v[26:27], v[6:7], v[170:171] op_sel_hi:[1,0,1]
	global_store_dwordx4 v[12:13], v[168:171], off offset:448
	s_waitcnt vmcnt(15)
	v_pk_fma_f32 v[172:173], v[28:29], v[6:7], v[172:173] op_sel_hi:[1,0,1]
	v_pk_fma_f32 v[174:175], v[30:31], v[6:7], v[174:175] op_sel_hi:[1,0,1]
	global_store_dwordx4 v[12:13], v[172:175], off offset:480
